# sg_sample part 1: VA/gamma/beta loads hoisted behind the first load, reloads become moves, wave_sum via permlane/DPP
# speedup vs baseline: 1.0203x; 1.0011x over previous
; #define LAS __attribute__((address_space(3)))
; __device__ __forceinline__ f32x4 unpack4(u32x2 u) { f32x4 r; r[0] = bflo(u[0]); r[1] = bfhi(u[0]); r[2] = bflo(u[1]); r[3] = bfhi(u[1]); return r; }
; __device__ __forceinline__ float wave_sum(float v) {
; #pragma unroll
;   for (int o = 32; o >= 1; o >>= 1) v += __shfl_xor(v, o);
;   return v;
; }
; __device__ __forceinline__ void mix_sg_sample(const Params& p, LAS unsigned char* lds, int b) {
;     ...
;   __syncthreads();
; #pragma unroll
;   for (int g = 0; g < 4; ++g) {
;     const int col = g * 256 + 4 * lane;
;     const f32x4 x = unpack4(*(const u32x2*)(VA + (size_t)(r0 + w) * 1024 + col));
;     const float mean = wave_sum(x[0] + x[1] + x[2] + x[3]) * (1.0f / 256.0f);
;     const f32x4 d = x - mean;
;     const float var = wave_sum(d[0] * d[0] + d[1] * d[1] + d[2] * d[2] + d[3] * d[3]) * (1.0f / 256.0f);
;     const float rstd = rsqrtf(var + LN_EPS);
;     const f32x4 gg = *(const f32x4*)(p.in[7] + col), bb = *(const f32x4*)(p.in[8] + col);
;     const f32x4 va = d * rstd * gg + bb;
;     *(f32x4*)(p.out + O_CV + (size_t)(b * 8 + w) * 1024 + col) = va;
;     *(LAS f32x4*)(vs + w * 1024 + col) = va;
;   }
.LBB0_193:
	s_add_i32 s29, s42, 0xff80
	s_and_b32 s34, s29, 0xffff
	s_mul_i32 s34, s34, 0xf0f1
	s_lshr_b32 s44, s34, 20
	s_mul_i32 s34, s44, 17
	s_sub_i32 s29, s29, s34
	s_and_b32 s43, s29, 0xffff
	s_cmp_gt_u32 s43, 7
	s_cbranch_scc0 .LBB0_232
	s_cmp_gt_u32 s43, 11
	s_cbranch_scc0 .LBB0_219
	s_cmp_gt_u32 s43, 13
	s_cbranch_scc0 .LBB0_216
	s_cmp_gt_u32 s43, 15
	s_cbranch_scc0 .LBB0_214
	v_and_b32_e32 v1, 64, v230
	v_add_u32_e32 v1, 64, v1
	v_xor_b32_e32 v4, 32, v230
	v_cmp_lt_i32_e32 vcc, v4, v1
	v_mov_b32_e32 v17, v226
	v_readlane_b32 s34, v252, 55
	v_cndmask_b32_e32 v4, v230, v4, vcc
	v_lshlrev_b32_e32 v7, 2, v4
	v_xor_b32_e32 v4, 16, v230
	v_cmp_lt_i32_e32 vcc, v4, v1
	v_ashrrev_i32_e32 v6, 6, v17
	v_lshlrev_b32_e32 v0, 2, v17
	v_cndmask_b32_e32 v4, v230, v4, vcc
	v_lshlrev_b32_e32 v19, 2, v4
	v_xor_b32_e32 v4, 8, v230
	v_cmp_lt_i32_e32 vcc, v4, v1
	v_and_b32_e32 v18, 0xfc, v0
	v_lshl_add_u32 v0, s44, 3, v6
	v_cndmask_b32_e32 v4, v230, v4, vcc
	v_lshlrev_b32_e32 v20, 2, v4
	v_xor_b32_e32 v4, 4, v230
	v_cmp_lt_i32_e32 vcc, v4, v1
	v_add_u32_e32 v8, 0x2000, v0
	v_ashrrev_i32_e32 v9, 31, v8
	v_cndmask_b32_e32 v4, v230, v4, vcc
	v_lshlrev_b32_e32 v21, 2, v4
	v_xor_b32_e32 v4, 2, v230
	v_cmp_lt_i32_e32 vcc, v4, v1
	v_lshlrev_b64 v[10:11], 11, v[8:9]
	v_readlane_b32 s35, v252, 56
	v_cndmask_b32_e32 v4, v230, v4, vcc
	v_lshlrev_b32_e32 v22, 2, v4
	v_xor_b32_e32 v4, 1, v230
	v_cmp_lt_i32_e32 vcc, v4, v1
	v_lshl_add_u64 v[2:3], s[34:35], 0, v[10:11]
	v_lshlrev_b32_e32 v64, 1, v18
	v_cndmask_b32_e32 v1, v230, v4, vcc
	v_lshlrev_b32_e32 v23, 2, v1
	v_ashrrev_i32_e32 v1, 31, v0
	v_lshlrev_b64 v[4:5], 12, v[0:1]
	v_lshl_add_u64 v[0:1], v[2:3], 0, v[64:65]
	s_barrier
	global_load_dwordx2 v[2:3], v[0:1], off
	s_mov_b32 s29, 0x800000
	v_readlane_b32 s48, v251, 0
	v_readlane_b32 s49, v251, 1
	v_readlane_b32 s34, v252, 59
	v_readlane_b32 s35, v252, 60
	v_lshlrev_b32_e32 v16, 12, v6
	v_readlane_b32 s52, v251, 4
	v_lshl_add_u64 v[4:5], s[34:35], 0, v[4:5]
	v_readlane_b32 s53, v251, 5
	v_readlane_b32 s50, v251, 2
	v_readlane_b32 s51, v251, 3
	v_readlane_b32 s54, v251, 6
	v_readlane_b32 s55, v251, 7
	v_readlane_b32 s56, v251, 8
	v_readlane_b32 s57, v251, 9
	v_readlane_b32 s58, v251, 10
	v_readlane_b32 s59, v251, 11
	v_readlane_b32 s60, v251, 12
	v_readlane_b32 s61, v251, 13
	v_readlane_b32 s62, v251, 14
	v_readlane_b32 s63, v251, 15
	global_load_dwordx2 v[144:145], v[0:1], off offset:512
	global_load_dwordx2 v[146:147], v[0:1], off offset:1024
	global_load_dwordx2 v[148:149], v[0:1], off offset:1536
	v_lshlrev_b32_e32 v142, 4, v230
	global_load_dwordx4 v[100:103], v142, s[18:19]
	global_load_dwordx4 v[104:107], v142, s[48:49]
	global_load_dwordx4 v[108:111], v142, s[18:19] offset:1024
	global_load_dwordx4 v[112:115], v142, s[48:49] offset:1024
	global_load_dwordx4 v[116:119], v142, s[18:19] offset:2048
	global_load_dwordx4 v[120:123], v142, s[48:49] offset:2048
	global_load_dwordx4 v[124:127], v142, s[18:19] offset:3072
	global_load_dwordx4 v[128:131], v142, s[48:49] offset:3072
	s_waitcnt vmcnt(0)
	v_lshlrev_b32_e32 v12, 16, v2
	v_and_b32_e32 v13, 0xffff0000, v2
	v_lshlrev_b32_e32 v14, 16, v3
	v_add_f32_e32 v2, v12, v13
	v_and_b32_e32 v15, 0xffff0000, v3
	v_add_f32_e32 v2, v2, v14
	v_add_f32_e32 v2, v2, v15
	v_mov_b32_e32 v3, v2
	s_nop 1
	v_permlane32_swap_b32_e32 v3, v2
	s_waitcnt lgkmcnt(0)
	v_add_f32_e32 v2, v2, v3
	v_mov_b32_e32 v3, v2
	s_nop 1
	v_permlane16_swap_b32_e32 v3, v2
	s_waitcnt lgkmcnt(0)
	v_add_f32_e32 v2, v2, v3
	s_nop 1
	v_mov_b32_dpp v3, v2 row_ror:8 row_mask:0xf bank_mask:0xf
	s_waitcnt lgkmcnt(0)
	v_add_f32_e32 v2, v2, v3
	s_nop 1
	v_mov_b32_dpp v3, v2 row_ror:4 row_mask:0xf bank_mask:0xf
	s_waitcnt lgkmcnt(0)
	v_add_f32_e32 v2, v2, v3
	s_nop 1
	v_mov_b32_dpp v3, v2 quad_perm:[2,3,0,1] row_mask:0xf bank_mask:0xf
	s_waitcnt lgkmcnt(0)
	v_add_f32_e32 v2, v2, v3
	s_nop 1
	v_mov_b32_dpp v3, v2 quad_perm:[1,0,3,2] row_mask:0xf bank_mask:0xf
	s_waitcnt lgkmcnt(0)
	v_add_f32_e32 v2, v2, v3
	v_fmac_f32_e32 v13, 0xbb800000, v2
	v_fmac_f32_e32 v12, 0xbb800000, v2
	v_fmac_f32_e32 v15, 0xbb800000, v2
	v_fmac_f32_e32 v14, 0xbb800000, v2
	v_pk_mul_f32 v[24:25], v[12:13], v[12:13]
	v_pk_mul_f32 v[2:3], v[14:15], v[14:15]
	v_add_f32_e32 v24, v24, v25
	v_add_f32_e32 v2, v2, v24
	v_add_f32_e32 v2, v3, v2
	v_mov_b32_e32 v3, v2
	s_nop 1
	v_permlane32_swap_b32_e32 v3, v2
	s_waitcnt lgkmcnt(0)
	v_add_f32_e32 v2, v2, v3
	v_mov_b32_e32 v3, v2
	s_nop 1
	v_permlane16_swap_b32_e32 v3, v2
	s_waitcnt lgkmcnt(0)
	v_add_f32_e32 v2, v2, v3
	s_nop 1
	v_mov_b32_dpp v3, v2 row_ror:8 row_mask:0xf bank_mask:0xf
	s_waitcnt lgkmcnt(0)
	v_add_f32_e32 v2, v2, v3
	s_nop 1
	v_mov_b32_dpp v3, v2 row_ror:4 row_mask:0xf bank_mask:0xf
	s_waitcnt lgkmcnt(0)
	v_add_f32_e32 v2, v2, v3
	s_nop 1
	v_mov_b32_dpp v3, v2 quad_perm:[2,3,0,1] row_mask:0xf bank_mask:0xf
	s_waitcnt lgkmcnt(0)
	v_add_f32_e32 v2, v2, v3
	s_nop 1
	v_mov_b32_dpp v3, v2 quad_perm:[1,0,3,2] row_mask:0xf bank_mask:0xf
	s_waitcnt lgkmcnt(0)
	v_add_f32_e32 v2, v2, v3
	v_fmamk_f32 v2, v2, 0x3b800000, v228
	v_cmp_gt_f32_e32 vcc, s29, v2
	v_mul_f32_e32 v3, 0x4b800000, v2
	s_nop 0
	v_cndmask_b32_e32 v2, v2, v3, vcc
	v_rsq_f32_e32 v2, v2
	s_nop 0
	v_mul_f32_e32 v3, 0x45800000, v2
	v_cndmask_b32_e32 v32, v2, v3, vcc
	v_lshlrev_b32_e32 v2, 2, v18
	s_nop 1
	v_mov_b64_e32 v[24:25], v[100:101]
	v_mov_b64_e32 v[26:27], v[102:103]
	s_nop 1
	v_mov_b64_e32 v[28:29], v[104:105]
	v_mov_b64_e32 v[30:31], v[106:107]
	v_mov_b32_e32 v3, v65
	v_pk_mul_f32 v[12:13], v[12:13], v[32:33] op_sel_hi:[1,0]
	v_pk_mul_f32 v[14:15], v[14:15], v[32:33] op_sel_hi:[1,0]
	v_lshl_add_u64 v[4:5], v[4:5], 0, v[2:3]
	v_add3_u32 v3, 0, v16, v2
	v_pk_fma_f32 v[14:15], v[26:27], v[14:15], v[30:31]
	v_pk_fma_f32 v[12:13], v[24:25], v[12:13], v[28:29]
	global_store_dwordx4 v[4:5], v[12:15], off
	ds_write_b128 v3, v[12:15]
	s_nop 1
	v_mov_b64_e32 v[14:15], v[144:145]
	v_lshlrev_b32_e32 v12, 16, v14
	v_and_b32_e32 v13, 0xffff0000, v14
	v_lshlrev_b32_e32 v14, 16, v15
	v_add_f32_e32 v16, v12, v13
	v_and_b32_e32 v15, 0xffff0000, v15
	v_add_f32_e32 v16, v16, v14
	v_add_f32_e32 v16, v16, v15
	v_mov_b32_e32 v24, v16
	s_nop 1
	v_permlane32_swap_b32_e32 v24, v16
	s_waitcnt lgkmcnt(0)
; #define LAS __attribute__((address_space(3)))
; __device__ __forceinline__ f32x4 unpack4(u32x2 u) { f32x4 r; r[0] = bflo(u[0]); r[1] = bfhi(u[0]); r[2] = bflo(u[1]); r[3] = bfhi(u[1]); return r; }
; __device__ __forceinline__ float wave_sum(float v) {
; #pragma unroll
;   for (int o = 32; o >= 1; o >>= 1) v += __shfl_xor(v, o);
;   return v;
; }
; __device__ __forceinline__ void mix_sg_sample(const Params& p, LAS unsigned char* lds, int b) {
;     ...
;   for (int g = 0; g < 4; ++g) {
;     const int col = g * 256 + 4 * lane;
;     const f32x4 x = unpack4(*(const u32x2*)(VA + (size_t)(r0 + w) * 1024 + col));
;     const float mean = wave_sum(x[0] + x[1] + x[2] + x[3]) * (1.0f / 256.0f);
;     const f32x4 d = x - mean;
;     const float var = wave_sum(d[0] * d[0] + d[1] * d[1] + d[2] * d[2] + d[3] * d[3]) * (1.0f / 256.0f);
;     const float rstd = rsqrtf(var + LN_EPS);
;     const f32x4 gg = *(const f32x4*)(p.in[7] + col), bb = *(const f32x4*)(p.in[8] + col);
;     const f32x4 va = d * rstd * gg + bb;
;     *(f32x4*)(p.out + O_CV + (size_t)(b * 8 + w) * 1024 + col) = va;
;     *(LAS f32x4*)(vs + w * 1024 + col) = va;
;   }
	v_add_f32_e32 v16, v16, v24
	v_mov_b32_e32 v24, v16
	s_nop 1
	v_permlane16_swap_b32_e32 v24, v16
	s_waitcnt lgkmcnt(0)
	v_add_f32_e32 v16, v16, v24
	s_nop 1
	v_mov_b32_dpp v24, v16 row_ror:8 row_mask:0xf bank_mask:0xf
	s_waitcnt lgkmcnt(0)
	v_add_f32_e32 v16, v16, v24
	s_nop 1
	v_mov_b32_dpp v24, v16 row_ror:4 row_mask:0xf bank_mask:0xf
	s_waitcnt lgkmcnt(0)
	v_add_f32_e32 v16, v16, v24
	s_nop 1
	v_mov_b32_dpp v24, v16 quad_perm:[2,3,0,1] row_mask:0xf bank_mask:0xf
	s_waitcnt lgkmcnt(0)
	v_add_f32_e32 v16, v16, v24
	s_nop 1
	v_mov_b32_dpp v24, v16 quad_perm:[1,0,3,2] row_mask:0xf bank_mask:0xf
	s_waitcnt lgkmcnt(0)
	v_add_f32_e32 v16, v16, v24
	v_fmac_f32_e32 v13, 0xbb800000, v16
	v_fmac_f32_e32 v12, 0xbb800000, v16
	v_fmac_f32_e32 v15, 0xbb800000, v16
	v_fmac_f32_e32 v14, 0xbb800000, v16
	v_pk_mul_f32 v[26:27], v[12:13], v[12:13]
	v_pk_mul_f32 v[24:25], v[14:15], v[14:15]
	v_add_f32_e32 v16, v26, v27
	v_add_f32_e32 v16, v24, v16
	v_add_f32_e32 v16, v25, v16
	v_mov_b32_e32 v24, v16
	s_nop 1
	v_permlane32_swap_b32_e32 v24, v16
	s_waitcnt lgkmcnt(0)
	v_add_f32_e32 v16, v16, v24
	v_mov_b32_e32 v24, v16
	s_nop 1
	v_permlane16_swap_b32_e32 v24, v16
	s_waitcnt lgkmcnt(0)
	v_add_f32_e32 v16, v16, v24
	s_nop 1
	v_mov_b32_dpp v24, v16 row_ror:8 row_mask:0xf bank_mask:0xf
	s_waitcnt lgkmcnt(0)
	v_add_f32_e32 v16, v16, v24
	s_nop 1
	v_mov_b32_dpp v24, v16 row_ror:4 row_mask:0xf bank_mask:0xf
	s_waitcnt lgkmcnt(0)
	v_add_f32_e32 v16, v16, v24
	s_nop 1
	v_mov_b32_dpp v24, v16 quad_perm:[2,3,0,1] row_mask:0xf bank_mask:0xf
	s_waitcnt lgkmcnt(0)
	v_add_f32_e32 v16, v16, v24
	s_nop 1
	v_mov_b32_dpp v24, v16 quad_perm:[1,0,3,2] row_mask:0xf bank_mask:0xf
	s_waitcnt lgkmcnt(0)
	v_add_f32_e32 v16, v16, v24
	v_fmamk_f32 v16, v16, 0x3b800000, v228
	v_cmp_gt_f32_e32 vcc, s29, v16
	v_mul_f32_e32 v24, 0x4b800000, v16
	s_nop 0
	v_cndmask_b32_e32 v16, v16, v24, vcc
	v_rsq_f32_e32 v16, v16
	s_nop 0
	v_mul_f32_e32 v24, 0x45800000, v16
	v_cndmask_b32_e32 v16, v16, v24, vcc
	s_nop 1
	v_mov_b64_e32 v[24:25], v[108:109]
	v_mov_b64_e32 v[26:27], v[110:111]
	s_nop 1
	v_mov_b64_e32 v[28:29], v[112:113]
	v_mov_b64_e32 v[30:31], v[114:115]
	v_pk_mul_f32 v[12:13], v[12:13], v[16:17] op_sel_hi:[1,0]
	v_pk_mul_f32 v[14:15], v[14:15], v[16:17] op_sel_hi:[1,0]
	v_pk_fma_f32 v[12:13], v[24:25], v[12:13], v[28:29]
	v_pk_fma_f32 v[14:15], v[26:27], v[14:15], v[30:31]
	global_store_dwordx4 v[4:5], v[12:15], off offset:1024
	ds_write_b128 v3, v[12:15] offset:1024
	s_nop 1
	v_mov_b64_e32 v[14:15], v[146:147]
	v_lshlrev_b32_e32 v12, 16, v14
	v_and_b32_e32 v13, 0xffff0000, v14
	v_lshlrev_b32_e32 v14, 16, v15
	v_add_f32_e32 v16, v12, v13
	v_and_b32_e32 v15, 0xffff0000, v15
	v_add_f32_e32 v16, v16, v14
	v_add_f32_e32 v16, v16, v15
	v_mov_b32_e32 v24, v16
	s_nop 1
	v_permlane32_swap_b32_e32 v24, v16
	s_waitcnt lgkmcnt(0)
	v_add_f32_e32 v16, v16, v24
	v_mov_b32_e32 v24, v16
	s_nop 1
	v_permlane16_swap_b32_e32 v24, v16
	s_waitcnt lgkmcnt(0)
	v_add_f32_e32 v16, v16, v24
	s_nop 1
	v_mov_b32_dpp v24, v16 row_ror:8 row_mask:0xf bank_mask:0xf
	s_waitcnt lgkmcnt(0)
	v_add_f32_e32 v16, v16, v24
	s_nop 1
	v_mov_b32_dpp v24, v16 row_ror:4 row_mask:0xf bank_mask:0xf
	s_waitcnt lgkmcnt(0)
	v_add_f32_e32 v16, v16, v24
	s_nop 1
	v_mov_b32_dpp v24, v16 quad_perm:[2,3,0,1] row_mask:0xf bank_mask:0xf
	s_waitcnt lgkmcnt(0)
	v_add_f32_e32 v16, v16, v24
	s_nop 1
	v_mov_b32_dpp v24, v16 quad_perm:[1,0,3,2] row_mask:0xf bank_mask:0xf
	s_waitcnt lgkmcnt(0)
	v_add_f32_e32 v16, v16, v24
	v_fmac_f32_e32 v13, 0xbb800000, v16
	v_fmac_f32_e32 v12, 0xbb800000, v16
	v_fmac_f32_e32 v15, 0xbb800000, v16
	v_fmac_f32_e32 v14, 0xbb800000, v16
	v_pk_mul_f32 v[26:27], v[12:13], v[12:13]
	v_pk_mul_f32 v[24:25], v[14:15], v[14:15]
	v_add_f32_e32 v16, v26, v27
	v_add_f32_e32 v16, v24, v16
	v_add_f32_e32 v16, v25, v16
	v_mov_b32_e32 v24, v16
	s_nop 1
	v_permlane32_swap_b32_e32 v24, v16
	s_waitcnt lgkmcnt(0)
	v_add_f32_e32 v16, v16, v24
	v_mov_b32_e32 v24, v16
	s_nop 1
	v_permlane16_swap_b32_e32 v24, v16
	s_waitcnt lgkmcnt(0)
	v_add_f32_e32 v16, v16, v24
	s_nop 1
	v_mov_b32_dpp v24, v16 row_ror:8 row_mask:0xf bank_mask:0xf
	s_waitcnt lgkmcnt(0)
	v_add_f32_e32 v16, v16, v24
	s_nop 1
	v_mov_b32_dpp v24, v16 row_ror:4 row_mask:0xf bank_mask:0xf
	s_waitcnt lgkmcnt(0)
	v_add_f32_e32 v16, v16, v24
	s_nop 1
	v_mov_b32_dpp v24, v16 quad_perm:[2,3,0,1] row_mask:0xf bank_mask:0xf
	s_waitcnt lgkmcnt(0)
	v_add_f32_e32 v16, v16, v24
	s_nop 1
	v_mov_b32_dpp v24, v16 quad_perm:[1,0,3,2] row_mask:0xf bank_mask:0xf
	s_waitcnt lgkmcnt(0)
; #define LAS __attribute__((address_space(3)))
; __device__ __forceinline__ f32x4 unpack4(u32x2 u) { f32x4 r; r[0] = bflo(u[0]); r[1] = bfhi(u[0]); r[2] = bflo(u[1]); r[3] = bfhi(u[1]); return r; }
; __device__ __forceinline__ void mix_sg_sample(const Params& p, LAS unsigned char* lds, int b) {
;     ...
;   for (int g = 0; g < 4; ++g) {
;     const int col = g * 256 + 4 * lane;
;     const f32x4 x = unpack4(*(const u32x2*)(VA + (size_t)(r0 + w) * 1024 + col));
;     const float mean = wave_sum(x[0] + x[1] + x[2] + x[3]) * (1.0f / 256.0f);
;     const f32x4 d = x - mean;
;     const float var = wave_sum(d[0] * d[0] + d[1] * d[1] + d[2] * d[2] + d[3] * d[3]) * (1.0f / 256.0f);
;     const float rstd = rsqrtf(var + LN_EPS);
;     const f32x4 gg = *(const f32x4*)(p.in[7] + col), bb = *(const f32x4*)(p.in[8] + col);
;     const f32x4 va = d * rstd * gg + bb;
;     *(f32x4*)(p.out + O_CV + (size_t)(b * 8 + w) * 1024 + col) = va;
;     *(LAS f32x4*)(vs + w * 1024 + col) = va;
;   }
;   __syncthreads();
; #pragma unroll
;   for (int g = 0; g < 4; ++g) {
;     const int col = g * 256 + 4 * lane;
;     const float bias = p.in[10][g * 128 + w];
;     f32x4 z = (f32x4){bias, bias, bias, bias};
;     for (int j = 0; j <= w; ++j) {
;       const float wv = p.in[9][((size_t)g * 128 + w) * 128 + j];
	v_add_f32_e32 v16, v16, v24
	v_fmamk_f32 v16, v16, 0x3b800000, v228
	v_cmp_gt_f32_e32 vcc, s29, v16
	v_mul_f32_e32 v24, 0x4b800000, v16
	s_nop 0
	v_cndmask_b32_e32 v16, v16, v24, vcc
	v_rsq_f32_e32 v16, v16
	s_nop 0
	v_mul_f32_e32 v24, 0x45800000, v16
	v_cndmask_b32_e32 v16, v16, v24, vcc
	s_nop 1
	v_mov_b64_e32 v[24:25], v[116:117]
	v_mov_b64_e32 v[26:27], v[118:119]
	s_nop 1
	v_mov_b64_e32 v[28:29], v[120:121]
	v_mov_b64_e32 v[30:31], v[122:123]
	v_pk_mul_f32 v[12:13], v[12:13], v[16:17] op_sel_hi:[1,0]
	v_pk_mul_f32 v[14:15], v[14:15], v[16:17] op_sel_hi:[1,0]
	v_pk_fma_f32 v[12:13], v[24:25], v[12:13], v[28:29]
	v_pk_fma_f32 v[14:15], v[26:27], v[14:15], v[30:31]
	global_store_dwordx4 v[4:5], v[12:15], off offset:2048
	s_nop 1
	v_mov_b64_e32 v[0:1], v[148:149]
	ds_write_b128 v3, v[12:15] offset:2048
	v_lshlrev_b32_e32 v24, 16, v0
	v_and_b32_e32 v25, 0xffff0000, v0
	v_lshlrev_b32_e32 v0, 16, v1
	v_add_f32_e32 v12, v24, v25
	v_and_b32_e32 v1, 0xffff0000, v1
	v_add_f32_e32 v12, v12, v0
	v_add_f32_e32 v12, v12, v1
	v_mov_b32_e32 v13, v12
	s_nop 1
	v_permlane32_swap_b32_e32 v13, v12
	s_waitcnt lgkmcnt(0)
	v_add_f32_e32 v12, v12, v13
	v_mov_b32_e32 v13, v12
	s_nop 1
	v_permlane16_swap_b32_e32 v13, v12
	s_waitcnt lgkmcnt(0)
	v_add_f32_e32 v12, v12, v13
	s_nop 1
	v_mov_b32_dpp v13, v12 row_ror:8 row_mask:0xf bank_mask:0xf
	s_waitcnt lgkmcnt(0)
	v_add_f32_e32 v12, v12, v13
	s_nop 1
	v_mov_b32_dpp v13, v12 row_ror:4 row_mask:0xf bank_mask:0xf
	s_waitcnt lgkmcnt(0)
	v_add_f32_e32 v12, v12, v13
	s_nop 1
	v_mov_b32_dpp v13, v12 quad_perm:[2,3,0,1] row_mask:0xf bank_mask:0xf
	s_waitcnt lgkmcnt(0)
	v_add_f32_e32 v12, v12, v13
	s_nop 1
	v_mov_b32_dpp v13, v12 quad_perm:[1,0,3,2] row_mask:0xf bank_mask:0xf
	s_waitcnt lgkmcnt(0)
	v_add_f32_e32 v12, v12, v13
	v_fmac_f32_e32 v25, 0xbb800000, v12
	v_fmac_f32_e32 v24, 0xbb800000, v12
	v_fmac_f32_e32 v1, 0xbb800000, v12
	v_fmac_f32_e32 v0, 0xbb800000, v12
	v_pk_mul_f32 v[14:15], v[24:25], v[24:25]
	v_pk_mul_f32 v[12:13], v[0:1], v[0:1]
	v_add_f32_e32 v14, v14, v15
	v_add_f32_e32 v12, v12, v14
	v_add_f32_e32 v12, v13, v12
	v_mov_b32_e32 v7, v12
	s_nop 1
	v_permlane32_swap_b32_e32 v7, v12
	s_waitcnt lgkmcnt(0)
	v_add_f32_e32 v7, v12, v7
	v_mov_b32_e32 v12, v7
	s_nop 1
	v_permlane16_swap_b32_e32 v12, v7
	s_waitcnt lgkmcnt(0)
	v_add_f32_e32 v7, v7, v12
	s_nop 1
	v_mov_b32_dpp v12, v7 row_ror:8 row_mask:0xf bank_mask:0xf
	s_waitcnt lgkmcnt(0)
	v_add_f32_e32 v7, v7, v12
	s_nop 1
	v_mov_b32_dpp v12, v7 row_ror:4 row_mask:0xf bank_mask:0xf
	s_waitcnt lgkmcnt(0)
	v_add_f32_e32 v7, v7, v12
	s_nop 1
	v_mov_b32_dpp v12, v7 quad_perm:[2,3,0,1] row_mask:0xf bank_mask:0xf
	s_waitcnt lgkmcnt(0)
	v_add_f32_e32 v7, v7, v12
	s_nop 1
	v_mov_b32_dpp v12, v7 quad_perm:[1,0,3,2] row_mask:0xf bank_mask:0xf
	s_waitcnt lgkmcnt(0)
	v_add_f32_e32 v7, v7, v12
	v_fmamk_f32 v7, v7, 0x3b800000, v228
	v_cmp_gt_f32_e32 vcc, s29, v7
	v_mul_f32_e32 v12, 0x4b800000, v7
	s_nop 0
	v_cndmask_b32_e32 v7, v7, v12, vcc
	v_rsq_f32_e32 v7, v7
	s_nop 0
	v_mul_f32_e32 v12, 0x45800000, v7
	v_cndmask_b32_e32 v16, v7, v12, vcc
	s_nop 1
	v_mov_b64_e32 v[12:13], v[124:125]
	v_mov_b64_e32 v[14:15], v[126:127]
	s_nop 1
	v_mov_b64_e32 v[20:21], v[128:129]
	v_mov_b64_e32 v[22:23], v[130:131]
	v_pk_mul_f32 v[24:25], v[24:25], v[16:17] op_sel_hi:[1,0]
	v_pk_mul_f32 v[0:1], v[0:1], v[16:17] op_sel_hi:[1,0]
	v_ashrrev_i32_e32 v7, 31, v6
	v_cmp_lt_i32_e32 vcc, -1, v6
	v_add_u32_e32 v16, 1, v6
	v_pk_fma_f32 v[14:15], v[14:15], v[0:1], v[22:23]
	v_pk_fma_f32 v[12:13], v[12:13], v[24:25], v[20:21]
	global_store_dwordx4 v[4:5], v[12:15], off offset:3072
	ds_write_b128 v3, v[12:15] offset:3072
	s_waitcnt lgkmcnt(0)
	v_lshl_add_u64 v[12:13], v[6:7], 2, s[52:53]
	s_barrier
	global_load_dword v0, v[12:13], off
	s_waitcnt vmcnt(0)
	v_mov_b32_e32 v1, v0
	v_mov_b64_e32 v[4:5], v[2:3]
	v_mov_b32_e32 v14, v0
	v_mov_b64_e32 v[2:3], v[0:1]
	s_and_saveexec_b64 s[38:39], vcc
	s_cbranch_execz .LBB0_201
	v_mov_b32_e32 v7, v65
	v_readlane_b32 s48, v251, 0
	v_lshlrev_b64 v[2:3], 9, v[6:7]
	v_readlane_b32 s50, v251, 2
	v_readlane_b32 s51, v251, 3
	v_lshl_add_u32 v4, v18, 2, 0
	v_add_u32_e32 v5, 1, v6
	v_lshl_add_u64 v[2:3], s[50:51], 0, v[2:3]
	s_mov_b64 s[40:41], 0
	v_mov_b32_e32 v1, v0
	v_mov_b32_e32 v14, v0
	v_mov_b32_e32 v15, v0
	v_readlane_b32 s49, v251, 1
	v_readlane_b32 s52, v251, 4
	v_readlane_b32 s53, v251, 5
	v_readlane_b32 s54, v251, 6
	v_readlane_b32 s55, v251, 7
	v_readlane_b32 s56, v251, 8
	v_readlane_b32 s57, v251, 9
	v_readlane_b32 s58, v251, 10
	v_readlane_b32 s59, v251, 11
	v_readlane_b32 s60, v251, 12
	v_readlane_b32 s61, v251, 13
	v_readlane_b32 s62, v251, 14
	v_readlane_b32 s63, v251, 15
